# phase W exact f32 head-row projections: all four waves of a group share an item (16 rows each) instead of one wave doing 64 rows while three idle
# speedup vs baseline: 1.0114x; 1.0022x over previous
; #define LAS __attribute__((address_space(3)))
; __device__ __forceinline__ void phase_W(CArgs& a, int l, LAS unsigned char* lds, const int tid, const int bx, const int G) {
;     ...
;         if ((gw & 3) == 0)
;         for (int it = gw >> 2; it < 512; it += (NGW + 3) >> 2) {
;             const int cg = it & 15, kc = it >> 4, k0 = kc * 32;
;             { const f32x4* xr = (const f32x4*)(xsrc + ((size_t)(lane >> 3) * SEQ + (lane & 7)) * DM + k0);
; #pragma unroll
;               for (int i = 0; i < 8; ++i) { const f32x4 v = xr[i]; *(LAS f32x4*)(xs + lane * 36 + 4 * i) = v; } }
;             float w[32];
;             { const float* Wl = a.in[I_WIN] + (size_t)l * DM * INW + (size_t)k0 * INW + 1536 + cg * 64 + lane; const float* gm = a.in[I_NMG] + l * DM + k0;
; #pragma unroll
;               for (int kk = 0; kk < 32; ++kk) w[kk] = Wl[(size_t)kk * INW] * gm[kk]; }
.LBB0_502:
	s_or_b64 exec, exec, s[50:51]
	s_cmp_eq_u32 s46, 0
	v_mov_b32_e32 v0, 0
	s_cselect_b64 s[4:5], -1, 0
	v_cmp_eq_u32_e32 vcc, 0, v0
	s_and_saveexec_b64 s[12:13], vcc
	s_cbranch_execz .LBB0_508
	v_ashrrev_i32_e32 v91, 2, v59
	s_movk_i32 s10, 0x200
	v_cmp_gt_i32_e32 vcc, s10, v91
	s_and_b64 exec, exec, vcc
	s_cbranch_execz .LBB0_508
	s_and_b64 s[10:11], s[4:5], exec
	s_cselect_b32 s10, 0, 0xa8
	s_add_u32 s10, s48, s10
	s_addc_u32 s11, s49, 0
	s_load_dwordx2 s[10:11], s[10:11], 0x0
	v_lshlrev_b32_e32 v0, 9, v58
	s_load_dwordx4 s[16:19], s[48:49], 0x10
	v_and_b32_e32 v2, 7, v61
	v_and_or_b32 v0, v0, s99, v2
	v_lshlrev_b32_e32 v0, 12, v0
	s_waitcnt lgkmcnt(0)
	v_lshl_add_u64 v[62:63], s[10:11], 0, v[0:1]
	s_mul_i32 s11, s46, 0x1900000
	s_mul_hi_i32 s10, s46, 0x1900000
	s_add_u32 s14, s18, s11
	s_addc_u32 s15, s19, s10
	s_lshl_b32 s10, s46, 10
	s_ashr_i32 s11, s10, 31
	s_lshl_b64 s[10:11], s[10:11], 2
	v_mul_u32_u24_e32 v2, 0x90, v58
	s_add_u32 s16, s16, s10
	v_lshlrev_b32_e32 v0, 2, v58
	s_addc_u32 s17, s17, s11
	s_lshl_b32 s10, s37, 1
	v_lshl_add_u64 v[64:65], s[6:7], 0, v[0:1]
	v_lshlrev_b32_e32 v92, 6, v91
	s_lshl_b32 s11, s37, 7
	s_mov_b64 s[18:19], 0
	v_add_u32_e32 v93, v90, v2
	v_lshlrev_b32_e32 v66, 2, v58
.LBB0_505:
	v_ashrrev_i32_e32 v68, 4, v91
	v_lshlrev_b32_e32 v34, 5, v68
	v_ashrrev_i32_e32 v35, 31, v34
	v_mov_b64_e32 v[38:39], s[14:15]
	v_lshlrev_b32_e32 v0, 8, v91
	v_lshlrev_b64 v[36:37], 2, v[34:35]
	v_mad_i64_i32 v[34:35], s[42:43], v34, s98, v[38:39]
	v_and_b32_e32 v0, 0xf00, v0
	v_lshl_add_u64 v[34:35], v[34:35], 0, v[0:1]
	v_mov_b32_e32 v67, v1
	v_lshl_add_u64 v[70:71], v[34:35], 0, v[66:67]
	s_movk_i32 s21, 0x1000
	v_add_co_u32_e32 v34, vcc, s21, v70
	v_lshl_add_u64 v[30:31], v[62:63], 0, v[36:37]
	s_nop 0
	v_addc_co_u32_e32 v35, vcc, 0, v71, vcc
	v_lshl_add_u64 v[80:81], s[16:17], 0, v[36:37]
	v_add_co_u32_e32 v36, vcc, s99, v70
	s_mov_b32 s21, 0xe000
	s_nop 0
	v_addc_co_u32_e32 v37, vcc, 0, v71, vcc
	v_add_co_u32_e32 v38, vcc, s21, v70
	s_mov_b32 s21, 0x14000
	s_nop 0
	v_addc_co_u32_e32 v39, vcc, 0, v71, vcc
	v_add_co_u32_e32 v40, vcc, s21, v70
	s_mov_b32 s21, 0x1a000
	s_nop 0
	v_addc_co_u32_e32 v41, vcc, 0, v71, vcc
	v_add_co_u32_e32 v42, vcc, s21, v70
	s_mov_b32 s21, 0x27000
	s_nop 0
	v_addc_co_u32_e32 v43, vcc, 0, v71, vcc
	v_add_co_u32_e32 v44, vcc, s75, v70
	global_load_dwordx4 v[2:5], v[30:31], off offset:48
	global_load_dwordx4 v[6:9], v[30:31], off offset:32
	global_load_dwordx4 v[10:13], v[30:31], off offset:16
	global_load_dwordx4 v[14:17], v[30:31], off
	global_load_dwordx4 v[18:21], v[30:31], off offset:112
	global_load_dwordx4 v[22:25], v[30:31], off offset:96
	global_load_dwordx4 v[26:29], v[30:31], off offset:80
	s_nop 0
	global_load_dwordx4 v[30:33], v[30:31], off offset:64
	v_addc_co_u32_e32 v45, vcc, 0, v71, vcc
	v_add_co_u32_e32 v46, vcc, s21, v70
	s_mov_b32 s21, 0x2d000
	s_nop 0
	v_addc_co_u32_e32 v47, vcc, 0, v71, vcc
	v_add_co_u32_e32 v48, vcc, s21, v70
	s_mov_b32 s21, 0x33000
	s_nop 0
	v_addc_co_u32_e32 v49, vcc, 0, v71, vcc
	v_add_co_u32_e32 v50, vcc, s21, v70
	s_mov_b32 s21, 0x39000
	s_nop 0
	v_addc_co_u32_e32 v51, vcc, 0, v71, vcc
	v_add_co_u32_e32 v52, vcc, s21, v70
	s_mov_b32 s21, 0x40000
	s_nop 0
	v_addc_co_u32_e32 v53, vcc, 0, v71, vcc
	v_add_co_u32_e32 v54, vcc, s21, v70
	s_mov_b32 s21, 0x46000
	s_nop 0
	v_addc_co_u32_e32 v55, vcc, 0, v71, vcc
	v_add_co_u32_e32 v56, vcc, s21, v70
	s_mov_b32 s21, 0x4c000
	s_nop 0
	v_addc_co_u32_e32 v57, vcc, 0, v71, vcc
	v_add_co_u32_e32 v94, vcc, s21, v70
	s_mov_b32 s21, 0x52000
	s_nop 0
	v_addc_co_u32_e32 v95, vcc, 0, v71, vcc
	v_add_co_u32_e32 v96, vcc, s21, v70
	s_mov_b32 s21, 0x59000
	s_nop 0
	v_addc_co_u32_e32 v97, vcc, 0, v71, vcc
	v_add_co_u32_e32 v98, vcc, s21, v70
	s_mov_b32 s21, 0x5f000
	s_nop 0
	v_addc_co_u32_e32 v99, vcc, 0, v71, vcc
	v_add_co_u32_e32 v100, vcc, s21, v70
	s_mov_b32 s21, 0x65000
	s_nop 0
	v_addc_co_u32_e32 v101, vcc, 0, v71, vcc
	global_load_dword v78, v[34:35], off offset:2048
	global_load_dword v76, v[36:37], off offset:3072
	global_load_dword v74, v[38:39], off
	global_load_dword v72, v[40:41], off offset:1024
	global_load_dword v79, v[42:43], off offset:2048
	global_load_dword v77, v[44:45], off offset:3072
	global_load_dword v75, v[46:47], off
	global_load_dword v73, v[48:49], off offset:1024
	global_load_dwordx4 v[34:37], v[80:81], off offset:48
	global_load_dwordx4 v[38:41], v[80:81], off offset:32
	s_nop 0
	global_load_dwordx4 v[42:45], v[80:81], off offset:16
	global_load_dwordx4 v[46:49], v[80:81], off
	global_load_dword v88, v[50:51], off offset:2048
	global_load_dword v86, v[52:53], off offset:3072
	global_load_dword v84, v[54:55], off
	global_load_dword v82, v[56:57], off offset:1024
	global_load_dword v89, v[94:95], off offset:2048
	global_load_dword v87, v[96:97], off offset:3072
	global_load_dword v85, v[98:99], off
	global_load_dword v83, v[100:101], off offset:1024
	v_add_co_u32_e32 v50, vcc, s21, v70
	s_mov_b32 s21, 0x6b000
	s_nop 0
	v_addc_co_u32_e32 v51, vcc, 0, v71, vcc
	v_add_co_u32_e32 v52, vcc, s21, v70
	s_mov_b32 s21, 0x72000
	s_nop 0
	v_addc_co_u32_e32 v53, vcc, 0, v71, vcc
	v_add_co_u32_e32 v54, vcc, s21, v70
	s_mov_b32 s21, 0x78000
	s_nop 0
	v_addc_co_u32_e32 v55, vcc, 0, v71, vcc
	v_add_co_u32_e32 v56, vcc, s21, v70
	s_mov_b32 s21, 0x7e000
	s_nop 0
	v_addc_co_u32_e32 v57, vcc, 0, v71, vcc
	v_add_co_u32_e32 v94, vcc, s21, v70
	s_mov_b32 s21, 0x84000
	s_nop 0
	v_addc_co_u32_e32 v95, vcc, 0, v71, vcc
	v_add_co_u32_e32 v96, vcc, s21, v70
	s_mov_b32 s21, 0x8b000
	s_nop 0
	v_addc_co_u32_e32 v97, vcc, 0, v71, vcc
	v_add_co_u32_e32 v98, vcc, s21, v70
	s_mov_b32 s21, 0x91000
	s_nop 0
	v_addc_co_u32_e32 v99, vcc, 0, v71, vcc
	v_add_co_u32_e32 v100, vcc, s21, v70
	s_mov_b32 s21, 0x97000
	s_nop 0
	v_addc_co_u32_e32 v101, vcc, 0, v71, vcc
	global_load_dword v102, v[50:51], off offset:2048
	global_load_dword v104, v[52:53], off offset:3072
	global_load_dword v106, v[54:55], off
	global_load_dword v108, v[56:57], off offset:1024
	global_load_dword v103, v[94:95], off offset:2048
	global_load_dword v105, v[96:97], off offset:3072
	global_load_dword v107, v[98:99], off
	global_load_dword v109, v[100:101], off offset:1024
	global_load_dwordx4 v[50:53], v[80:81], off offset:112
	global_load_dwordx4 v[54:57], v[80:81], off offset:96
	s_nop 0
	global_load_dwordx4 v[94:97], v[80:81], off offset:80
	global_load_dwordx4 v[98:101], v[80:81], off offset:64
	v_add_co_u32_e32 v80, vcc, s21, v70
	s_mov_b32 s21, 0x9d000
	s_nop 0
	v_addc_co_u32_e32 v81, vcc, 0, v71, vcc
	v_add_co_u32_e32 v110, vcc, s21, v70
	s_mov_b32 s21, 0xa4000
	s_nop 0
	v_addc_co_u32_e32 v111, vcc, 0, v71, vcc
	v_add_co_u32_e32 v112, vcc, s21, v70
	s_mov_b32 s21, 0xaa000
	s_nop 0
	v_addc_co_u32_e32 v113, vcc, 0, v71, vcc
	s_waitcnt vmcnt(0)
; #define LAS __attribute__((address_space(3)))
; #define LDS_WAIT() asm volatile("s_waitcnt lgkmcnt(0)" ::: "memory")
; __device__ __forceinline__ void phase_W(CArgs& a, int l, LAS unsigned char* lds, const int tid, const int bx, const int G) {
;     ...
;               for (int i = 0; i < 8; ++i) { const f32x4 v = xr[i]; *(LAS f32x4*)(xs + lane * 36 + 4 * i) = v; } }
;             float w[32];
;             { const float* Wl = a.in[I_WIN] + (size_t)l * DM * INW + (size_t)k0 * INW + 1536 + cg * 64 + lane; const float* gm = a.in[I_NMG] + l * DM + k0;
; #pragma unroll
;               for (int kk = 0; kk < 32; ++kk) w[kk] = Wl[(size_t)kk * INW] * gm[kk]; }
;             LDS_WAIT(); asm volatile("" ::: "memory");
; #pragma unroll 4
;             for (int r = 0; r < 64; ++r) { float acc = 0.f;
; #pragma unroll
;                 for (int k4 = 0; k4 < 8; ++k4) { const f32x4 xv = *(const LAS f32x4*)(xs + r * 36 + 4 * k4); acc += xv.x * w[4 * k4] + xv.y * w[4 * k4 + 1] + xv.z * w[4 * k4 + 2] + xv.w * w[4 * k4 + 3]; }
;                 part[((size_t)kc * 64 + r) * 1024 + cg * 64 + lane] = acc; }
	v_add_co_u32_e32 v114, vcc, s21, v70
	s_mov_b32 s21, 0xb0000
	s_nop 0
	v_addc_co_u32_e32 v115, vcc, 0, v71, vcc
	v_add_co_u32_e32 v116, vcc, s21, v70
	s_mov_b32 s21, 0xb6000
	s_nop 0
	v_addc_co_u32_e32 v117, vcc, 0, v71, vcc
	v_add_co_u32_e32 v118, vcc, s21, v70
	s_mov_b32 s21, 0xbd000
	s_nop 0
	v_addc_co_u32_e32 v119, vcc, 0, v71, vcc
	global_load_dword v80, v[80:81], off offset:2048
	s_nop 0
	global_load_dword v110, v[110:111], off offset:3072
	s_nop 0
	global_load_dword v81, v[116:117], off offset:2048
	global_load_dword v111, v[118:119], off offset:3072
	v_add_co_u32_e32 v116, vcc, s21, v70
	s_mov_b32 s21, 0xc3000
	s_nop 0
	v_addc_co_u32_e32 v117, vcc, 0, v71, vcc
	v_add_co_u32_e32 v70, vcc, s21, v70
	v_ashrrev_i32_e32 v69, 31, v68
	s_nop 0
	v_addc_co_u32_e32 v71, vcc, 0, v71, vcc
	global_load_dword v112, v[112:113], off
	s_nop 0
	global_load_dword v113, v[116:117], off
	s_nop 0
	global_load_dword v114, v[114:115], off offset:1024
	s_nop 0
	global_load_dword v115, v[70:71], off offset:1024
	ds_write_b128 v93, v[14:17]
	ds_write_b128 v93, v[10:13] offset:16
	ds_write_b128 v93, v[6:9] offset:32
	ds_write_b128 v93, v[2:5] offset:48
	ds_write_b128 v93, v[30:33] offset:64
	ds_write_b128 v93, v[26:29] offset:80
	ds_write_b128 v93, v[22:25] offset:96
	ds_write_b128 v93, v[18:21] offset:112
	v_mov_b32_e32 v11, v34
	v_mov_b32_e32 v34, v39
	s_waitcnt lgkmcnt(0)
	v_lshlrev_b32_e32 v0, 2, v92
	v_pk_mul_f32 v[12:13], v[86:87], v[34:35]
	v_lshlrev_b64 v[34:35], 18, v[68:69]
	s_movk_i32 s21, 0xf00
	v_mov_b32_e32 v2, v46
	v_mov_b32_e32 v3, v42
	v_mov_b32_e32 v42, v47
	v_mov_b32_e32 v6, v48
	v_mov_b32_e32 v7, v44
	v_mov_b32_e32 v44, v49
	v_mov_b32_e32 v10, v38
	v_mov_b32_e32 v14, v40
	v_mov_b32_e32 v15, v36
	v_mov_b32_e32 v36, v41
	v_and_or_b32 v34, v0, s21, v34
	v_pk_mul_f32 v[2:3], v[78:79], v[2:3]
	v_pk_mul_f32 v[4:5], v[76:77], v[42:43]
	v_pk_mul_f32 v[6:7], v[74:75], v[6:7]
	v_pk_mul_f32 v[8:9], v[72:73], v[44:45]
	v_pk_mul_f32 v[10:11], v[88:89], v[10:11]
	v_pk_mul_f32 v[14:15], v[84:85], v[14:15]
	v_pk_mul_f32 v[16:17], v[82:83], v[36:37]
	v_lshl_add_u64 v[34:35], v[64:65], 0, v[34:35]
	s_and_b32 s95, s3, 3
	s_mul_i32 s96, s95, 0x900
	s_lshl_b32 s50, s95, 16
	s_mov_b32 s51, 0
	s_add_u32 s95, s50, 0x10000
	v_add_u32_e32 v0, s96, v90
	v_mov_b32_e32 v27, v50
	v_mov_b32_e32 v26, v54
	v_mov_b32_e32 v19, v94
	v_mov_b32_e32 v18, v98
	v_mov_b32_e32 v94, v99
	v_mov_b32_e32 v22, v100
	v_mov_b32_e32 v23, v96
	v_mov_b32_e32 v96, v101
	v_mov_b32_e32 v50, v55
	v_mov_b32_e32 v30, v56
	v_mov_b32_e32 v31, v52
	v_mov_b32_e32 v52, v57
	v_pk_mul_f32 v[18:19], v[102:103], v[18:19]
	v_pk_mul_f32 v[20:21], v[104:105], v[94:95]
	v_pk_mul_f32 v[22:23], v[106:107], v[22:23]
	v_pk_mul_f32 v[24:25], v[108:109], v[96:97]
	s_waitcnt vmcnt(5)
	v_pk_mul_f32 v[26:27], v[80:81], v[26:27]
	s_waitcnt vmcnt(4)
	v_pk_mul_f32 v[28:29], v[110:111], v[50:51]
	s_waitcnt vmcnt(2)
	v_pk_mul_f32 v[30:31], v[112:113], v[30:31]
	s_waitcnt vmcnt(0)
	v_pk_mul_f32 v[32:33], v[114:115], v[52:53]
.LBB0_506:
	ds_read_b128 v[36:39], v0
	ds_read_b128 v[40:43], v0 offset:16
	ds_read_b128 v[44:47], v0 offset:32
	ds_read_b128 v[48:51], v0 offset:48
	s_mov_b32 s21, 0x1f601000
	s_waitcnt lgkmcnt(3)
	v_mov_b32_e32 v52, v36
	s_waitcnt lgkmcnt(2)
	v_mov_b32_e32 v53, v40
	v_mov_b32_e32 v40, v37
	v_pk_mul_f32 v[36:37], v[4:5], v[40:41]
	v_mov_b32_e32 v40, v38
	v_pk_fma_f32 v[36:37], v[2:3], v[52:53], v[36:37]
	v_mov_b32_e32 v41, v42
	v_pk_fma_f32 v[36:37], v[6:7], v[40:41], v[36:37]
	v_mov_b32_e32 v42, v39
	v_pk_fma_f32 v[36:37], v[8:9], v[42:43], v[36:37]
	s_nop 0
	v_add_f32_e32 v36, 0, v36
	v_add_f32_e32 v40, v36, v37
	s_waitcnt lgkmcnt(0)
	v_mov_b32_e32 v37, v48
	v_mov_b32_e32 v48, v45
	v_mov_b32_e32 v36, v44
	v_pk_mul_f32 v[38:39], v[12:13], v[48:49]
	s_nop 0
	v_pk_fma_f32 v[36:37], v[10:11], v[36:37], v[38:39]
	v_mov_b32_e32 v38, v46
	v_mov_b32_e32 v39, v50
	v_pk_fma_f32 v[36:37], v[14:15], v[38:39], v[36:37]
	v_mov_b32_e32 v50, v47
	v_pk_fma_f32 v[36:37], v[16:17], v[50:51], v[36:37]
	s_nop 0
	v_add_f32_e32 v36, v40, v36
	v_add_f32_e32 v46, v36, v37
	ds_read_b128 v[36:39], v0 offset:64
	ds_read_b128 v[40:43], v0 offset:80
	s_waitcnt lgkmcnt(1)
	v_mov_b32_e32 v44, v36
	s_waitcnt lgkmcnt(0)
	v_mov_b32_e32 v45, v40
	v_mov_b32_e32 v40, v37
	v_pk_mul_f32 v[36:37], v[20:21], v[40:41]
	v_mov_b32_e32 v40, v38
	v_pk_fma_f32 v[36:37], v[18:19], v[44:45], v[36:37]
	v_mov_b32_e32 v41, v42
	v_pk_fma_f32 v[36:37], v[22:23], v[40:41], v[36:37]
	v_mov_b32_e32 v42, v39
	v_pk_fma_f32 v[36:37], v[24:25], v[42:43], v[36:37]
	s_nop 0
	v_add_f32_e32 v36, v46, v36
	v_add_f32_e32 v46, v36, v37
	ds_read_b128 v[36:39], v0 offset:96
	ds_read_b128 v[40:43], v0 offset:112
	s_waitcnt lgkmcnt(1)
	v_mov_b32_e32 v44, v36
	s_waitcnt lgkmcnt(0)
	v_mov_b32_e32 v45, v40
	v_mov_b32_e32 v40, v37
	v_pk_mul_f32 v[36:37], v[28:29], v[40:41]
	v_mov_b32_e32 v40, v38
	v_pk_fma_f32 v[36:37], v[26:27], v[44:45], v[36:37]
	v_mov_b32_e32 v41, v42
	v_pk_fma_f32 v[36:37], v[30:31], v[40:41], v[36:37]
	v_mov_b32_e32 v42, v39
	v_pk_fma_f32 v[36:37], v[32:33], v[42:43], v[36:37]
	s_nop 0
	v_add_f32_e32 v36, v46, v36
	v_add_f32_e32 v40, v36, v37
	v_lshl_add_u64 v[36:37], v[34:35], 0, s[50:51]
	v_add_co_u32_e32 v38, vcc, s21, v36
	s_mov_b32 s21, 0x1f602000
	s_nop 0
	v_addc_co_u32_e32 v39, vcc, 0, v37, vcc
	global_store_dword v[38:39], v40, off offset:-4096
	ds_read_b128 v[40:43], v0 offset:144
	ds_read_b128 v[44:47], v0 offset:160
	s_add_u32 s50, s50, 0x4000
	s_addc_u32 s51, s51, 0
	s_cmp_lg_u32 s50, s95
	s_waitcnt lgkmcnt(1)
	v_mov_b32_e32 v48, v40
	s_waitcnt lgkmcnt(0)
; #define LAS __attribute__((address_space(3)))
; #define LDS_WAIT() asm volatile("s_waitcnt lgkmcnt(0)" ::: "memory")
; __device__ __forceinline__ void phase_W(CArgs& a, int l, LAS unsigned char* lds, const int tid, const int bx, const int G) {
;     ...
;         for (int it = gw >> 2; it < 512; it += (NGW + 3) >> 2) {
;     ...
;             for (int r = 0; r < 64; ++r) { float acc = 0.f;
; #pragma unroll
;                 for (int k4 = 0; k4 < 8; ++k4) { const f32x4 xv = *(const LAS f32x4*)(xs + r * 36 + 4 * k4); acc += xv.x * w[4 * k4] + xv.y * w[4 * k4 + 1] + xv.z * w[4 * k4 + 2] + xv.w * w[4 * k4 + 3]; }
;                 part[((size_t)kc * 64 + r) * 1024 + cg * 64 + lane] = acc; }
;             LDS_WAIT(); asm volatile("" ::: "memory");
;         }
	v_mov_b32_e32 v49, v44
	v_mov_b32_e32 v44, v41
	v_pk_mul_f32 v[40:41], v[4:5], v[44:45]
	v_mov_b32_e32 v44, v42
	v_pk_fma_f32 v[40:41], v[2:3], v[48:49], v[40:41]
	v_mov_b32_e32 v45, v46
	v_pk_fma_f32 v[40:41], v[6:7], v[44:45], v[40:41]
	v_mov_b32_e32 v46, v43
	v_pk_fma_f32 v[40:41], v[8:9], v[46:47], v[40:41]
	s_nop 0
	v_add_f32_e32 v40, 0, v40
	v_add_f32_e32 v50, v40, v41
	ds_read_b128 v[40:43], v0 offset:176
	ds_read_b128 v[44:47], v0 offset:192
	s_waitcnt lgkmcnt(1)
	v_mov_b32_e32 v48, v40
	s_waitcnt lgkmcnt(0)
	v_mov_b32_e32 v49, v44
	v_mov_b32_e32 v44, v41
	v_pk_mul_f32 v[40:41], v[12:13], v[44:45]
	v_mov_b32_e32 v44, v42
	v_pk_fma_f32 v[40:41], v[10:11], v[48:49], v[40:41]
	v_mov_b32_e32 v45, v46
	v_pk_fma_f32 v[40:41], v[14:15], v[44:45], v[40:41]
	v_mov_b32_e32 v46, v43
	v_pk_fma_f32 v[40:41], v[16:17], v[46:47], v[40:41]
	s_nop 0
	v_add_f32_e32 v40, v50, v40
	v_add_f32_e32 v50, v40, v41
	ds_read_b128 v[40:43], v0 offset:208
	ds_read_b128 v[44:47], v0 offset:224
	s_waitcnt lgkmcnt(1)
	v_mov_b32_e32 v48, v40
	s_waitcnt lgkmcnt(0)
	v_mov_b32_e32 v49, v44
	v_mov_b32_e32 v44, v41
	v_pk_mul_f32 v[40:41], v[20:21], v[44:45]
	v_mov_b32_e32 v44, v42
	v_pk_fma_f32 v[40:41], v[18:19], v[48:49], v[40:41]
	v_mov_b32_e32 v45, v46
	v_pk_fma_f32 v[40:41], v[22:23], v[44:45], v[40:41]
	v_mov_b32_e32 v46, v43
	v_pk_fma_f32 v[40:41], v[24:25], v[46:47], v[40:41]
	s_nop 0
	v_add_f32_e32 v40, v50, v40
	v_add_f32_e32 v50, v40, v41
	ds_read_b128 v[40:43], v0 offset:240
	ds_read_b128 v[44:47], v0 offset:256
	s_waitcnt lgkmcnt(1)
	v_mov_b32_e32 v48, v40
	s_waitcnt lgkmcnt(0)
	v_mov_b32_e32 v49, v44
	v_mov_b32_e32 v44, v41
	v_pk_mul_f32 v[40:41], v[28:29], v[44:45]
	v_mov_b32_e32 v44, v42
	v_pk_fma_f32 v[40:41], v[26:27], v[48:49], v[40:41]
	v_mov_b32_e32 v45, v46
	v_pk_fma_f32 v[40:41], v[30:31], v[44:45], v[40:41]
	v_mov_b32_e32 v46, v43
	v_pk_fma_f32 v[40:41], v[32:33], v[46:47], v[40:41]
	s_nop 0
	v_add_f32_e32 v40, v50, v40
	v_add_f32_e32 v40, v40, v41
	global_store_dword v[38:39], v40, off
	ds_read_b128 v[38:41], v0 offset:288
	ds_read_b128 v[42:45], v0 offset:304
	ds_read_b128 v[46:49], v0 offset:320
	ds_read_b128 v[50:53], v0 offset:336
	s_waitcnt lgkmcnt(3)
	v_mov_b32_e32 v54, v38
	s_waitcnt lgkmcnt(2)
	v_mov_b32_e32 v55, v42
	v_mov_b32_e32 v42, v39
	v_pk_mul_f32 v[38:39], v[4:5], v[42:43]
	v_mov_b32_e32 v42, v40
	v_pk_fma_f32 v[38:39], v[2:3], v[54:55], v[38:39]
	v_mov_b32_e32 v43, v44
	v_pk_fma_f32 v[38:39], v[6:7], v[42:43], v[38:39]
	v_mov_b32_e32 v44, v41
	v_pk_fma_f32 v[38:39], v[8:9], v[44:45], v[38:39]
	s_nop 0
	v_add_f32_e32 v38, 0, v38
	v_add_f32_e32 v42, v38, v39
	s_waitcnt lgkmcnt(0)
	v_mov_b32_e32 v39, v50
	v_mov_b32_e32 v50, v47
	v_mov_b32_e32 v38, v46
	v_pk_mul_f32 v[40:41], v[12:13], v[50:51]
	s_nop 0
	v_pk_fma_f32 v[38:39], v[10:11], v[38:39], v[40:41]
	v_mov_b32_e32 v40, v48
	v_mov_b32_e32 v41, v52
	v_pk_fma_f32 v[38:39], v[14:15], v[40:41], v[38:39]
	v_mov_b32_e32 v52, v49
	v_pk_fma_f32 v[38:39], v[16:17], v[52:53], v[38:39]
	s_nop 0
	v_add_f32_e32 v38, v42, v38
	v_add_f32_e32 v48, v38, v39
	ds_read_b128 v[38:41], v0 offset:352
	ds_read_b128 v[42:45], v0 offset:368
	s_waitcnt lgkmcnt(1)
	v_mov_b32_e32 v46, v38
	s_waitcnt lgkmcnt(0)
	v_mov_b32_e32 v47, v42
	v_mov_b32_e32 v42, v39
	v_pk_mul_f32 v[38:39], v[20:21], v[42:43]
	v_mov_b32_e32 v42, v40
	v_pk_fma_f32 v[38:39], v[18:19], v[46:47], v[38:39]
	v_mov_b32_e32 v43, v44
	v_pk_fma_f32 v[38:39], v[22:23], v[42:43], v[38:39]
	v_mov_b32_e32 v44, v41
	v_pk_fma_f32 v[38:39], v[24:25], v[44:45], v[38:39]
	s_nop 0
	v_add_f32_e32 v38, v48, v38
	v_add_f32_e32 v48, v38, v39
	ds_read_b128 v[38:41], v0 offset:384
	ds_read_b128 v[42:45], v0 offset:400
	s_waitcnt lgkmcnt(1)
	v_mov_b32_e32 v46, v38
	s_waitcnt lgkmcnt(0)
	v_mov_b32_e32 v47, v42
	v_mov_b32_e32 v42, v39
	v_pk_mul_f32 v[38:39], v[28:29], v[42:43]
	v_mov_b32_e32 v42, v40
	v_pk_fma_f32 v[38:39], v[26:27], v[46:47], v[38:39]
	v_mov_b32_e32 v43, v44
	v_pk_fma_f32 v[38:39], v[30:31], v[42:43], v[38:39]
	v_mov_b32_e32 v44, v41
	v_pk_fma_f32 v[38:39], v[32:33], v[44:45], v[38:39]
	s_nop 0
	v_add_f32_e32 v38, v48, v38
	v_add_f32_e32 v40, v38, v39
	v_add_co_u32_e32 v38, vcc, s21, v36
	s_nop 1
	v_addc_co_u32_e32 v39, vcc, 0, v37, vcc
	global_store_dword v[38:39], v40, off
	ds_read_b128 v[38:41], v0 offset:432
	ds_read_b128 v[42:45], v0 offset:448
	v_add_co_u32_e32 v36, vcc, 0x1f603000, v36
	s_waitcnt lgkmcnt(1)
	v_mov_b32_e32 v46, v38
	s_waitcnt lgkmcnt(0)
	v_mov_b32_e32 v47, v42
	v_mov_b32_e32 v42, v39
	v_pk_mul_f32 v[38:39], v[4:5], v[42:43]
	v_mov_b32_e32 v42, v40
	v_pk_fma_f32 v[38:39], v[2:3], v[46:47], v[38:39]
	v_mov_b32_e32 v43, v44
	v_pk_fma_f32 v[38:39], v[6:7], v[42:43], v[38:39]
	v_mov_b32_e32 v44, v41
	v_pk_fma_f32 v[38:39], v[8:9], v[44:45], v[38:39]
	v_addc_co_u32_e32 v37, vcc, 0, v37, vcc
	v_add_f32_e32 v38, 0, v38
	v_add_f32_e32 v48, v38, v39
	ds_read_b128 v[38:41], v0 offset:464
	ds_read_b128 v[42:45], v0 offset:480
	s_waitcnt lgkmcnt(1)
	v_mov_b32_e32 v46, v38
	s_waitcnt lgkmcnt(0)
	v_mov_b32_e32 v47, v42
	v_mov_b32_e32 v42, v39
	v_pk_mul_f32 v[38:39], v[12:13], v[42:43]
	v_mov_b32_e32 v42, v40
	v_pk_fma_f32 v[38:39], v[10:11], v[46:47], v[38:39]
	v_mov_b32_e32 v43, v44
	v_pk_fma_f32 v[38:39], v[14:15], v[42:43], v[38:39]
	v_mov_b32_e32 v44, v41
	v_pk_fma_f32 v[38:39], v[16:17], v[44:45], v[38:39]
	s_nop 0
	v_add_f32_e32 v38, v48, v38
	v_add_f32_e32 v48, v38, v39
	ds_read_b128 v[38:41], v0 offset:496
	ds_read_b128 v[42:45], v0 offset:512
	s_waitcnt lgkmcnt(1)
	v_mov_b32_e32 v46, v38
	s_waitcnt lgkmcnt(0)
	v_mov_b32_e32 v47, v42
	v_mov_b32_e32 v42, v39
	v_pk_mul_f32 v[38:39], v[20:21], v[42:43]
	v_mov_b32_e32 v42, v40
	v_pk_fma_f32 v[38:39], v[18:19], v[46:47], v[38:39]
	v_mov_b32_e32 v43, v44
	v_pk_fma_f32 v[38:39], v[22:23], v[42:43], v[38:39]
	v_mov_b32_e32 v44, v41
	v_pk_fma_f32 v[38:39], v[24:25], v[44:45], v[38:39]
	s_nop 0
	v_add_f32_e32 v38, v48, v38
	v_add_f32_e32 v48, v38, v39
	ds_read_b128 v[38:41], v0 offset:528
	ds_read_b128 v[42:45], v0 offset:544
	v_add_u32_e32 v0, 0x240, v0
	s_waitcnt lgkmcnt(1)
	v_mov_b32_e32 v46, v38
	s_waitcnt lgkmcnt(0)
	v_mov_b32_e32 v47, v42
	v_mov_b32_e32 v42, v39
	v_pk_mul_f32 v[38:39], v[28:29], v[42:43]
	v_mov_b32_e32 v42, v40
	v_pk_fma_f32 v[38:39], v[26:27], v[46:47], v[38:39]
	v_mov_b32_e32 v43, v44
	v_pk_fma_f32 v[38:39], v[30:31], v[42:43], v[38:39]
	v_mov_b32_e32 v44, v41
	v_pk_fma_f32 v[38:39], v[32:33], v[44:45], v[38:39]
	s_nop 0
	v_add_f32_e32 v38, v48, v38
	v_add_f32_e32 v38, v38, v39
	global_store_dword v[36:37], v38, off
	s_cbranch_scc1 .LBB0_506
	s_waitcnt lgkmcnt(0)
	v_add_u32_e32 v91, s10, v91
	s_movk_i32 s21, 0x1ff
	v_cmp_lt_i32_e32 vcc, s21, v91
	s_or_b64 s[18:19], vcc, s[18:19]
	v_add_u32_e32 v92, s11, v92
	s_andn2_b64 exec, exec, s[18:19]
	s_cbranch_execnz .LBB0_505
